# LRU pass prologues: first super-chunk row loads issued together with the gate-weight loads (before the weight wait and log1p chain)
# speedup vs baseline: 1.0119x; 1.0035x over previous
; #define LAS __attribute__((address_space(3)))
; template <int dir>
; __device__ __forceinline__ void lru_pass(LAS unsigned char* lds, const Params& P, int b, int h, int q, bool dry) {
;     ...
;     {
; #pragma unroll
;         for (int i = 0; i < 2; ++i) { const int idx = tid + i * NTHREADS, gate = idx >> 9, n = (idx >> 4) & 31, kc = idx & 15;
;             *(LAS u32x4*)(WB + (gate * 32 + n) * XC_PITCH + kc * 16) = *(const u32x4*)(LruW + ((size_t)((dir * 2 + gate) * 8 + h) * 128 + q * 32 + n) * 128 + kc * 8); }
;         const float br = -LOG2E * P.lru_ba[(dir * 8 + h) * 128 + chl], bi = -LOG2E * P.lru_bx[(dir * 8 + h) * 128 + chl];
;         const float lam = P.lru_lambda[dir * 1024 + ch];
;         const float cl = -8.0f * LOG2E * log1pf(__expf(-lam));
;         float carry = 0.f;
;         LruTile cur = lru_tile(Z, ZC, b, h, dir, 0);
;         u32x4 rows[11];
;         constexpr int NIN = dir == 0 ? 2 : 4;
;         u32x4 inr[NIN];
;         lru_load_rows(rows, cur, tr, cgp);
.LBB0_291:
	s_or_b64 exec, exec, s[14:15]
	v_mov_b32_e32 v12, v167
	s_lshl_b32 s0, s25, 5
	s_waitcnt lgkmcnt(0)
	s_barrier
	s_and_b32 s28, s0, 0x60
	v_and_b32_e32 v15, 31, v12
	v_or_b32_e32 v17, s28, v15
	v_add_u32_e32 v14, 0x200, v12
	v_or_b32_e32 v11, s27, v17
	v_ashrrev_i32_e32 v8, 9, v12
	v_ashrrev_i32_e32 v10, 9, v14
	v_lshlrev_b32_e32 v16, 2, v11
	v_and_b32_e32 v13, 15, v12
	v_lshl_or_b32 v2, v8, 3, s26
	v_lshl_or_b32 v6, v10, 3, s26
	global_load_dword v18, v16, s[64:65]
	v_bfe_u32 v9, v12, 4, 5
	v_lshlrev_b32_e32 v64, 4, v13
	v_ashrrev_i32_e32 v3, 31, v2
	v_ashrrev_i32_e32 v7, 31, v6
	v_or_b32_e32 v4, s28, v9
	v_lshl_add_u64 v[0:1], s[38:39], 0, v[64:65]
	v_lshlrev_b64 v[2:3], 15, v[2:3]
	v_lshlrev_b64 v[6:7], 15, v[6:7]
	v_lshlrev_b32_e32 v4, 8, v4
	v_mov_b32_e32 v5, v65
	v_lshl_add_u64 v[2:3], v[0:1], 0, v[2:3]
	v_lshl_add_u64 v[0:1], v[0:1], 0, v[6:7]
	v_lshl_add_u64 v[2:3], v[2:3], 0, v[4:5]
	v_lshl_add_u64 v[4:5], v[0:1], 0, v[4:5]
	global_load_dwordx4 v[0:3], v[2:3], off
	s_nop 0
	global_load_dwordx4 v[4:7], v[4:5], off
	v_lshlrev_b32_e32 v11, 2, v12
	v_lshl_or_b32 v21, v8, 5, v9
	v_add_u32_e32 v8, s88, v64
	v_lshl_or_b32 v9, v10, 5, v9
	v_and_b32_e32 v22, 16, v11
	v_mad_u64_u32 v[10:11], s[4:5], v21, s89, v[8:9]
	v_mad_u64_u32 v[8:9], s[4:5], v9, s89, v[8:9]
	global_load_dword v9, v16, s[58:59]
	global_load_dword v11, v16, s[62:63]
	s_lshl_b32 s0, s2, 5
	s_and_b32 s0, s0, 0xe0
	s_or_b32 s1, s0, s25
	s_ashr_i32 s78, s1, 5
	s_ashr_i32 s79, s78, 31
	s_lshl_b32 s20, s26, 22
	s_lshl_b64 s[18:19], s[78:79], 19
	s_lshl_b64 s[44:45], s[78:79], 23
	v_readlane_b32 s1, v255, 18
	s_add_u32 s1, s1, s44
	s_addc_u32 s4, s33, s45
	s_lshl_b32 s5, s27, 2
	s_add_u32 s1, s1, s5
	s_addc_u32 s4, s4, 0
	s_add_u32 s5, s68, s18
	s_addc_u32 s6, s69, s19
	s_lshl_b32 s7, s27, 1
	s_add_u32 s48, s5, s7
	s_addc_u32 s49, s6, 0
	s_add_u32 s50, s48, 0x1000
	s_addc_u32 s51, s49, 0
	s_add_u32 s56, s48, 0x1800
	s_addc_u32 s57, s49, 0
	s_add_u32 s60, s48, 0x2000
	s_addc_u32 s61, s49, 0
	s_add_u32 s66, s48, 0x2800
	s_addc_u32 s67, s49, 0
	s_add_u32 s70, s48, 0x3000
	s_addc_u32 s71, s49, 0
	v_ashrrev_i32_e32 v36, 4, v12
	v_lshlrev_b32_e32 v37, 3, v13
	s_add_u32 s72, s48, 0x3800
	s_addc_u32 s73, s49, 0
	s_add_u32 s74, s48, 0x4000
	s_addc_u32 s75, s49, 0
	s_add_u32 s76, s48, 0x4800
	s_addc_u32 s77, s49, 0
	v_readfirstlane_b32 s0, v12
	s_ashr_i32 s6, s0, 6
	s_lshl_b32 s5, s28, 2
	s_add_u32 s8, s1, s5
	v_bfe_u32 v19, v12, 5, 1
	v_lshrrev_b32_e32 v20, 1, v12
	v_and_b32_e32 v33, 3, v12
	s_addc_u32 s9, s4, 0
	v_lshl_or_b32 v110, v36, 13, v37
	v_mov_b32_e32 v111, v65
	v_lshlrev_b64 v[110:111], 1, v[110:111]
	v_lshl_add_u64 v[108:109], s[48:49], 0, v[110:111]
	global_load_dwordx4 v[68:71], v[108:109], off offset:-2048
	global_load_dwordx4 v[72:75], v[108:109], off
	global_load_dwordx4 v[76:79], v[108:109], off offset:2048
	v_lshl_add_u64 v[108:109], s[50:51], 0, v[110:111]
	global_load_dwordx4 v[80:83], v[108:109], off
	v_lshl_add_u64 v[108:109], s[56:57], 0, v[110:111]
	global_load_dwordx4 v[84:87], v[108:109], off
	v_lshl_add_u64 v[108:109], s[60:61], 0, v[110:111]
	global_load_dwordx4 v[88:91], v[108:109], off
	v_lshl_add_u64 v[108:109], s[66:67], 0, v[110:111]
	global_load_dwordx4 v[92:95], v[108:109], off
	v_lshl_add_u64 v[108:109], s[70:71], 0, v[110:111]
	global_load_dwordx4 v[96:99], v[108:109], off
	v_lshl_add_u64 v[108:109], s[72:73], 0, v[110:111]
	global_load_dwordx4 v[100:103], v[108:109], off
	v_lshl_add_u64 v[108:109], s[74:75], 0, v[110:111]
	global_load_dwordx4 v[104:107], v[108:109], off
	v_lshl_add_u64 v[108:109], s[76:77], 0, v[110:111]
	global_load_dwordx4 v[108:111], v[108:109], off
	s_waitcnt vmcnt(14)
	ds_write_b128 v10, v[0:3]
	s_waitcnt vmcnt(13)
; #define LAS __attribute__((address_space(3)))
; template <int dir>
; __device__ __forceinline__ void lru_pass(LAS unsigned char* lds, const Params& P, int b, int h, int q, bool dry) {
;     ...
;         for (int i = 0; i < 2; ++i) { const int idx = tid + i * NTHREADS, gate = idx >> 9, n = (idx >> 4) & 31, kc = idx & 15;
;             *(LAS u32x4*)(WB + (gate * 32 + n) * XC_PITCH + kc * 16) = *(const u32x4*)(LruW + ((size_t)((dir * 2 + gate) * 8 + h) * 128 + q * 32 + n) * 128 + kc * 8); }
;         const float br = -LOG2E * P.lru_ba[(dir * 8 + h) * 128 + chl], bi = -LOG2E * P.lru_bx[(dir * 8 + h) * 128 + chl];
;         const float lam = P.lru_lambda[dir * 1024 + ch];
;         const float cl = -8.0f * LOG2E * log1pf(__expf(-lam));
;         float carry = 0.f;
;         LruTile cur = lru_tile(Z, ZC, b, h, dir, 0);
;         u32x4 rows[11];
;         constexpr int NIN = dir == 0 ? 2 : 4;
;         u32x4 inr[NIN];
;         lru_load_rows(rows, cur, tr, cgp);
	ds_write_b128 v8, v[4:7]
	v_mul_f32_e32 v16, 0xbfb8aa3b, v18
	v_exp_f32_e32 v16, v16
	s_lshl_b32 s1, s6, 5
	s_and_b32 s0, s0, 0x3fffffc0
	v_add_u32_e32 v39, 0, v64
	v_add_f32_e32 v2, 1.0, v16
	v_add_f32_e32 v3, -1.0, v2
	v_frexp_mant_f32_e32 v4, v2
	v_cvt_f64_f32_e32 v[0:1], v2
	v_sub_f32_e32 v5, v3, v2
	v_frexp_exp_i32_f64_e32 v0, v[0:1]
	v_cmp_gt_f32_e32 vcc, s80, v4
	v_sub_f32_e32 v3, v16, v3
	v_add_f32_e32 v1, 1.0, v5
	v_subbrev_co_u32_e32 v0, vcc, 0, v0, vcc
	v_add_f32_e32 v1, v3, v1
	v_sub_u32_e32 v3, 0, v0
	v_ldexp_f32 v2, v2, v3
	v_ldexp_f32 v1, v1, v3
	v_add_f32_e32 v3, -1.0, v2
	v_add_f32_e32 v4, 1.0, v2
	v_add_f32_e32 v5, 1.0, v3
	v_add_f32_e32 v6, -1.0, v4
	v_sub_f32_e32 v5, v2, v5
	v_sub_f32_e32 v2, v2, v6
	v_add_f32_e32 v5, v1, v5
	v_add_f32_e32 v1, v1, v2
	v_add_f32_e32 v6, v4, v1
	v_rcp_f32_e32 v7, v6
	v_add_f32_e32 v2, v3, v5
	v_sub_f32_e32 v4, v6, v4
	v_sub_f32_e32 v3, v2, v3
	v_sub_f32_e32 v1, v1, v4
	v_mul_f32_e32 v4, v2, v7
	v_sub_f32_e32 v3, v5, v3
	v_mul_f32_e32 v5, v6, v4
	v_fma_f32 v8, v4, v6, -v5
	v_fmac_f32_e32 v8, v4, v1
	v_add_f32_e32 v10, v5, v8
	v_sub_f32_e32 v18, v2, v10
	v_sub_f32_e32 v2, v2, v18
	v_sub_f32_e32 v5, v10, v5
	v_sub_f32_e32 v2, v2, v10
	v_sub_f32_e32 v5, v5, v8
	v_add_f32_e32 v2, v3, v2
	v_add_f32_e32 v2, v5, v2
	v_add_f32_e32 v3, v18, v2
	v_mul_f32_e32 v5, v7, v3
	v_mul_f32_e32 v10, v6, v5
	v_fma_f32 v6, v5, v6, -v10
	v_fmac_f32_e32 v6, v5, v1
	v_add_f32_e32 v1, v10, v6
	v_sub_f32_e32 v8, v18, v3
	v_sub_f32_e32 v18, v3, v1
	v_sub_f32_e32 v3, v3, v18
	v_add_f32_e32 v2, v2, v8
	v_sub_f32_e32 v10, v1, v10
	v_sub_f32_e32 v1, v3, v1
	v_sub_f32_e32 v6, v10, v6
	v_add_f32_e32 v1, v2, v1
	v_cvt_f32_i32_e32 v0, v0
	v_add_f32_e32 v8, v4, v5
	v_add_f32_e32 v1, v6, v1
	v_add_f32_e32 v1, v18, v1
	v_sub_f32_e32 v2, v8, v4
	v_mul_f32_e32 v1, v7, v1
	v_sub_f32_e32 v2, v5, v2
	v_add_f32_e32 v1, v2, v1
	v_mul_f32_e32 v5, 0x3f317218, v0
	v_add_f32_e32 v2, v8, v1
	v_fma_f32 v6, v0, s81, -v5
	v_fmac_f32_e32 v6, 0xb102e308, v0
	v_sub_f32_e32 v0, v2, v8
	v_mul_f32_e32 v3, v2, v2
	v_sub_f32_e32 v0, v1, v0
	v_add_f32_e32 v1, v5, v6
	v_fmamk_f32 v4, v3, 0x3e9b6dac, v200
	v_sub_f32_e32 v5, v1, v5
	v_fmaak_f32 v4, v3, v4, 0x3f2aaada
	v_sub_f32_e32 v5, v6, v5
	v_ldexp_f32 v6, v2, 1
	v_mul_f32_e32 v2, v2, v3
	v_mul_f32_e32 v2, v2, v4
	v_add_f32_e32 v3, v6, v2
	v_sub_f32_e32 v4, v3, v6
	v_ldexp_f32 v0, v0, 1
	v_sub_f32_e32 v2, v2, v4
	v_add_f32_e32 v0, v0, v2
	v_add_f32_e32 v2, v3, v0
	v_sub_f32_e32 v3, v2, v3
	v_sub_f32_e32 v0, v0, v3
	v_add_f32_e32 v3, v1, v2
	v_sub_f32_e32 v4, v3, v1
	v_sub_f32_e32 v6, v3, v4
	v_sub_f32_e32 v1, v1, v6
	v_sub_f32_e32 v2, v2, v4
	v_add_f32_e32 v1, v2, v1
	v_add_f32_e32 v2, v5, v0
	v_sub_f32_e32 v4, v2, v5
	v_add_f32_e32 v1, v2, v1
	v_sub_f32_e32 v6, v2, v4
	v_add_f32_e32 v2, v3, v1
	v_sub_f32_e32 v5, v5, v6
	v_sub_f32_e32 v0, v0, v4
	v_sub_f32_e32 v3, v2, v3
	v_add_f32_e32 v0, v0, v5
	v_sub_f32_e32 v1, v1, v3
	v_add_f32_e32 v0, v0, v1
	v_add_f32_e32 v0, v2, v0
	v_cmp_neq_f32_e32 vcc, s91, v16
	v_mov_b32_e32 v1, v65
	v_lshlrev_b32_e32 v41, 4, v19
	v_cndmask_b32_e32 v0, v201, v0, vcc
	v_cmp_ngt_f32_e32 vcc, -1.0, v16
	s_cmp_eq_u32 s6, 7
	v_or_b32_e32 v35, s1, v41
	v_cndmask_b32_e32 v0, v202, v0, vcc
	v_cmp_neq_f32_e32 vcc, -1.0, v16
	v_ashrrev_i32_e32 v32, 2, v12
	v_ashrrev_i32_e32 v34, 2, v14
	v_cndmask_b32_e32 v0, v203, v0, vcc
	v_cmp_lt_f32_e64 vcc, |v16|, s92
	v_lshlrev_b32_e32 v53, 4, v33
	v_mul_lo_u32 v48, v32, s87
	v_cndmask_b32_e32 v6, v0, v16, vcc
	v_lshlrev_b32_e32 v1, 2, v15
	v_lshlrev_b32_e32 v2, 4, v12
	v_add_u32_e32 v140, s94, v1
	v_and_b32_e32 v3, 48, v2
	v_and_b32_e32 v64, 0x70, v2
	v_and_or_b32 v2, v20, 12, v33
	v_or3_b32 v2, v2, v22, s1
	v_lshl_add_u32 v147, s0, 2, v140
	s_cselect_b64 s[0:1], -1, 0
	s_cmp_eq_u32 s6, 6
	s_cselect_b64 s[16:17], -1, 0
	s_cmp_eq_u32 s6, 5
	s_cselect_b64 s[4:5], -1, 0
	s_cmp_eq_u32 s6, 4
	v_lshl_add_u64 v[130:131], s[8:9], 0, v[64:65]
	s_cselect_b64 s[8:9], -1, 0
	s_cmp_eq_u32 s6, 3
	s_cselect_b64 s[10:11], -1, 0
	s_cmp_eq_u32 s6, 2
	s_cselect_b64 s[12:13], -1, 0
	s_cmp_eq_u32 s6, 1
	s_cselect_b64 s[14:15], -1, 0
	s_add_u32 s46, s20, s18
	s_addc_u32 s47, 0, s19
	s_lshl_b32 s6, s2, 3
	v_ashrrev_i32_e32 v33, 31, v32
	v_mul_lo_u32 v50, v35, s89
	v_mul_lo_u32 v51, v35, s87
	v_mul_lo_u32 v52, v35, s30
	v_ashrrev_i32_e32 v35, 31, v34
	s_bfe_u32 s29, s2, 0x20003
	s_and_b32 s6, s6, 0xc0
	v_lshlrev_b64 v[32:33], 8, v[32:33]
	v_mul_lo_u32 v2, v2, s89
	v_add_u32_e32 v46, s96, v1
	v_mul_lo_u32 v49, v34, s87
	v_add_u32_e32 v1, 0x400, v12
	v_lshlrev_b64 v[34:35], 8, v[34:35]
	v_lshl_add_u64 v[32:33], s[46:47], 0, v[32:33]
	s_add_u32 s18, s82, s46
	v_lshlrev_b32_e32 v38, 5, v13
	v_add_u32_e32 v129, s96, v64
	v_add_u32_e32 v42, 0, v2
	v_mov_b32_e32 v2, s88
	v_ashrrev_i32_e32 v143, 3, v1
	v_add_u32_e32 v1, 0x600, v12
	v_lshl_add_u64 v[34:35], s[46:47], 0, v[34:35]
	v_or3_b32 v32, v32, s6, v53
	v_lshl_or_b32 v64, v36, 10, v37
	s_addc_u32 s19, s83, s47
	v_mov_b32_e32 v66, v65
	v_mov_b32_e32 v67, v65
	s_waitcnt vmcnt(12)
	v_mul_f32_e32 v0, 0xbfb8aa3b, v9
	s_waitcnt vmcnt(11)
	v_mul_f32_e32 v16, 0xbfb8aa3b, v11
	v_add_u32_e32 v40, s95, v3
	v_mad_u32_u24 v43, v15, s89, v2
	v_lshl_add_u32 v44, v17, 1, 0
	v_lshl_add_u32 v45, v15, 1, s95
	v_mul_lo_u32 v47, v36, s93
	v_ashrrev_i32_e32 v148, 3, v12
	v_ashrrev_i32_e32 v145, 3, v14
	v_ashrrev_i32_e32 v141, 3, v1
	v_or3_b32 v34, v34, s6, v53
	v_lshl_add_u64 v[134:135], s[40:41], 0, v[32:33]
	v_lshl_add_u64 v[136:137], v[64:65], 1, s[18:19]
	v_mov_b32_e32 v64, v65
	v_add_u32_e32 v32, 0, v38
	v_mov_b64_e32 v[114:115], v[66:67]
	v_mov_b64_e32 v[118:119], v[66:67]
	s_mov_b32 s90, 0
	v_mul_f32_e32 v138, 0xc138aa3b, v6
	v_lshl_add_u32 v139, v36, 3, -1
	v_cmp_eq_u32_e32 vcc, 0, v19
	v_mul_lo_u32 v149, v148, s30
	v_mul_lo_u32 v146, v145, s30
	v_mul_lo_u32 v144, v143, s30
	v_mul_lo_u32 v142, v141, s30
	v_mov_b32_e32 v1, v0
	v_mov_b32_e32 v2, v0
	v_mov_b32_e32 v3, v0
	v_mov_b32_e32 v4, v0
	v_mov_b32_e32 v5, v0
	v_mov_b32_e32 v6, v0
	v_mov_b32_e32 v7, v0
	v_mov_b32_e32 v8, v0
	v_mov_b32_e32 v9, v0
	v_mov_b32_e32 v10, v0
	v_mov_b32_e32 v11, v0
	v_mov_b32_e32 v12, v0
	v_mov_b32_e32 v13, v0
	v_mov_b32_e32 v14, v0
	v_mov_b32_e32 v15, v0
	v_mov_b32_e32 v17, v16
	v_mov_b32_e32 v18, v16
	v_mov_b32_e32 v19, v16
	v_mov_b32_e32 v20, v16
	v_mov_b32_e32 v21, v16
	v_mov_b32_e32 v22, v16
	v_mov_b32_e32 v23, v16
	v_mov_b32_e32 v24, v16
	v_mov_b32_e32 v25, v16
	v_mov_b32_e32 v26, v16
	v_mov_b32_e32 v27, v16
	v_mov_b32_e32 v28, v16
	v_mov_b32_e32 v29, v16
	v_mov_b32_e32 v30, v16
	v_mov_b32_e32 v31, v16
	v_lshl_add_u64 v[132:133], s[40:41], 0, v[34:35]
	s_movk_i32 s92, 0x100
	v_mov_b32_e32 v165, 0
	s_mov_b64 s[80:81], 0
	v_add_u32_e32 v150, 0x15c00, v32
	v_add_u32_e32 v151, v39, v47
	v_add_u32_e32 v158, v40, v48
	v_add_u32_e32 v159, v40, v49
	v_add_u32_e32 v160, v42, v41
	v_add_u32_e32 v161, v43, v41
	v_add_u32_e32 v162, v44, v50
	v_add_u32_e32 v163, v45, v51
	v_add_u32_e32 v164, v46, v52
	v_mov_b64_e32 v[112:113], v[64:65]
	v_mov_b64_e32 v[116:117], v[64:65]
	s_mov_b32 s91, 0
	s_mov_b32 s93, 0
	s_mov_b32 s97, 0

; #define LAS __attribute__((address_space(3)))
; template <int dir>
; __device__ __forceinline__ void lru_pass(LAS unsigned char* lds, const Params& P, int b, int h, int q, bool dry) {
;     ...
;     {
; #pragma unroll
;         for (int i = 0; i < 2; ++i) { const int idx = tid + i * NTHREADS, gate = idx >> 9, n = (idx >> 4) & 31, kc = idx & 15;
;             *(LAS u32x4*)(WB + (gate * 32 + n) * XC_PITCH + kc * 16) = *(const u32x4*)(LruW + ((size_t)((dir * 2 + gate) * 8 + h) * 128 + q * 32 + n) * 128 + kc * 8); }
;         const float br = -LOG2E * P.lru_ba[(dir * 8 + h) * 128 + chl], bi = -LOG2E * P.lru_bx[(dir * 8 + h) * 128 + chl];
;         const float lam = P.lru_lambda[dir * 1024 + ch];
;         const float cl = -8.0f * LOG2E * log1pf(__expf(-lam));
;         float carry = 0.f;
;         LruTile cur = lru_tile(Z, ZC, b, h, dir, 0);
;         u32x4 rows[11];
;         constexpr int NIN = dir == 0 ? 2 : 4;
;         u32x4 inr[NIN];
;         lru_load_rows(rows, cur, tr, cgp);
;     ...
;         if (dir == 0) {
; #pragma unroll
;             for (int i = 0; i < 4; ++i) { const int id = tid + i * NTHREADS; *(u32x4*)(Hg + (size_t)(t0_prev + (id >> 3)) * DM + (id & 7) * 4) = *(const LAS u32x4*)(TOUT + (id >> 3) * IO_WP + (id & 7) * 16); }
;         } else if (!dry) {
; #pragma unroll
;             for (int i = 0; i < 2; ++i) { const int id = tid + i * NTHREADS; *(u32x4*)(Z + ZSLAB(8 + h, (size_t)b * SEQ + t0_prev + (id >> 2)) + q * 32 + (id & 3) * 8) = *(const LAS u32x4*)(TOUT + (id >> 2) * IO_NP + (id & 3) * 16); }
;         }
;     }
; }
; __device__ __forceinline__ void lru_strip(LAS unsigned char* lds, const Params& P, int strip, bool dry) {
;     const int tid = opaque_tid();
;     const int b = strip >> 5, h = (strip >> 2) & 7, q = strip & 3;
;     LAS float* CWL = (LAS float*)(lds + 256 * XC_PITCH + 2048 + 64 * XC_PITCH);
;     for (int i = tid; i < 640; i += NTHREADS) { const int k = i >> 7, c = i & 127; CWL[i] = k < 4 ? P.conv_w[k * 1024 + h * 128 + c] : P.conv_b[h * 128 + c]; }
;     LDS_BARRIER();
;     lru_pass<0>(lds, P, b, h, q, dry);
;     asm volatile("s_waitcnt vmcnt(0)" ::: "memory"); __syncthreads();
;     if (tid < 64) { __builtin_amdgcn_fence(__ATOMIC_ACQUIRE, "agent"); asm volatile("s_waitcnt vmcnt(0)" ::: "memory"); }
;     __syncthreads();
;     lru_pass<1>(lds, P, b, h, q, dry);
.LBB0_303:
	s_waitcnt lgkmcnt(0)
	s_barrier
	v_add_u32_e32 v0, v129, v149
	ds_read_b128 v[0:3], v0
	v_add_u32_e32 v4, s97, v148
	v_ashrrev_i32_e32 v5, 31, v4
	v_lshlrev_b64 v[4:5], 12, v[4:5]
	v_lshl_add_u64 v[8:9], v[130:131], 0, v[4:5]
	v_add_u32_e32 v4, v129, v146
	ds_read_b128 v[4:7], v4
	s_waitcnt lgkmcnt(1)
	global_store_dwordx4 v[8:9], v[0:3], off
	v_cmp_gt_i32_e32 vcc, 64, v128
	s_nop 0
	v_add_u32_e32 v0, s97, v145
	v_ashrrev_i32_e32 v1, 31, v0
	v_lshlrev_b64 v[0:1], 12, v[0:1]
	v_lshl_add_u64 v[0:1], v[130:131], 0, v[0:1]
	s_waitcnt lgkmcnt(0)
	global_store_dwordx4 v[0:1], v[4:7], off
	v_add_u32_e32 v0, v129, v144
	ds_read_b128 v[0:3], v0
	v_add_u32_e32 v4, s97, v143
	v_ashrrev_i32_e32 v5, 31, v4
	v_lshlrev_b64 v[4:5], 12, v[4:5]
	v_lshl_add_u64 v[8:9], v[130:131], 0, v[4:5]
	v_add_u32_e32 v4, v129, v142
	ds_read_b128 v[4:7], v4
	s_waitcnt lgkmcnt(1)
	global_store_dwordx4 v[8:9], v[0:3], off
	s_nop 1
	v_add_u32_e32 v0, s97, v141
	v_ashrrev_i32_e32 v1, 31, v0
	v_lshlrev_b64 v[0:1], 12, v[0:1]
	v_lshl_add_u64 v[0:1], v[130:131], 0, v[0:1]
	s_waitcnt lgkmcnt(0)
	global_store_dwordx4 v[0:1], v[4:7], off
	s_waitcnt lgkmcnt(0)
	v_mov_b32_e32 v32, v167
	s_barrier
	s_or_b32 s0, s26, 16
	v_and_b32_e32 v15, 31, v32
	v_or_b32_e32 v17, s28, v15
	v_add_u32_e32 v13, 0x200, v32
	v_or_b32_e32 v8, s27, v17
	v_ashrrev_i32_e32 v11, 9, v32
	v_ashrrev_i32_e32 v14, 9, v13
	v_lshlrev_b32_e32 v8, 2, v8
	v_mov_b32_e32 v9, v65
	v_lshl_add_u32 v2, v11, 3, s0
	v_lshl_add_u32 v6, v14, 3, s0
	v_lshl_add_u64 v[8:9], s[64:65], 0, v[8:9]
	s_movk_i32 s0, 0x1000
	v_add_co_u32_e32 v8, vcc, s0, v8
	v_and_b32_e32 v12, 15, v32
	s_nop 0
	v_addc_co_u32_e32 v9, vcc, 0, v9, vcc
	global_load_dword v16, v[8:9], off
	v_bfe_u32 v10, v32, 4, 5
	v_lshlrev_b32_e32 v64, 4, v12
	v_ashrrev_i32_e32 v3, 31, v2
	v_ashrrev_i32_e32 v7, 31, v6
	v_or_b32_e32 v4, s28, v10
	v_lshl_add_u64 v[0:1], s[38:39], 0, v[64:65]
	v_lshlrev_b64 v[2:3], 15, v[2:3]
	v_lshlrev_b64 v[6:7], 15, v[6:7]
	v_lshlrev_b32_e32 v4, 8, v4
	v_mov_b32_e32 v5, v65
	v_lshl_add_u64 v[2:3], v[0:1], 0, v[2:3]
	v_lshl_add_u64 v[0:1], v[0:1], 0, v[6:7]
	v_lshl_add_u64 v[2:3], v[2:3], 0, v[4:5]
	v_lshl_add_u64 v[4:5], v[0:1], 0, v[4:5]
	global_load_dwordx4 v[0:3], v[2:3], off
	s_nop 0
	global_load_dwordx4 v[4:7], v[4:5], off
	v_lshrrev_b32_e32 v8, 1, v32
	v_lshlrev_b32_e32 v9, 2, v32
	v_and_b32_e32 v20, 12, v8
	v_lshl_or_b32 v11, v11, 5, v10
	v_add_u32_e32 v8, s88, v64
	v_lshl_or_b32 v14, v14, 5, v10
	v_mad_u64_u32 v[10:11], s[6:7], v11, s89, v[8:9]
	s_or_b32 s8, s26, 8
	v_and_or_b32 v20, v9, 16, v20
	v_lshlrev_b32_e32 v21, 2, v17
	v_mad_u64_u32 v[8:9], s[6:7], v14, s89, v[8:9]
	v_lshl_or_b32 v9, s8, 9, v21
	global_load_dword v14, v9, s[58:59]
	s_nop 0
	global_load_dword v9, v9, s[62:63]
	s_mov_b32 s80, 0x3f2aaaab
	s_mov_b32 s81, 0x3f317218
	s_mov_b32 s91, 0x7f800000
	s_mov_b32 s92, 0x33800000
	v_ashrrev_i32_e32 v33, 4, v32
	v_lshlrev_b32_e32 v34, 3, v12
	v_readfirstlane_b32 s4, v32
	s_lshl_b64 s[0:1], s[78:79], 11
	s_lshl_b32 s5, s8, 14
	s_ashr_i32 s6, s4, 6
	s_add_u32 s26, s0, s5
	s_addc_u32 s27, s1, 0
	s_lshl_b32 s0, s28, 1
	v_readlane_b32 s1, v255, 10
	v_and_b32_e32 v19, 3, v32
	s_add_u32 s0, s1, s0
	v_bfe_u32 v18, v32, 5, 1
	v_add_u32_e32 v44, 0, v64
	v_lshlrev_b32_e32 v64, 4, v19
	s_addc_u32 s1, s3, 0
	v_lshl_add_u64 v[136:137], s[0:1], 0, v[64:65]
	s_lshl_b32 s0, s6, 5
	v_lshlrev_b32_e32 v46, 4, v18
	v_or_b32_e32 v37, s0, v46
	v_add_u32_e32 v158, s86, v64
	v_or_b32_e32 v64, 4, v37
	s_movk_i32 s93, 0x880
	v_ashrrev_i32_e32 v36, 3, v32
	v_ashrrev_i32_e32 v38, 3, v13
	v_ashrrev_i32_e32 v140, 2, v32
	v_sub_u32_e32 v39, 0xff, v37
	v_sub_u32_e32 v64, 0xff, v64
	v_lshl_add_u32 v160, v33, 3, -1
	v_mul_lo_u32 v52, v33, s93
	v_lshl_or_b32 v110, v33, 13, v34
	v_mov_b32_e32 v111, v65
	v_lshlrev_b64 v[110:111], 1, v[110:111]
	v_lshl_add_u64 v[108:109], s[48:49], 0, v[110:111]
	global_load_dwordx4 v[68:71], v[108:109], off offset:-2048
	global_load_dwordx4 v[72:75], v[108:109], off
	global_load_dwordx4 v[76:79], v[108:109], off offset:2048
	v_lshl_add_u64 v[108:109], s[50:51], 0, v[110:111]
	global_load_dwordx4 v[80:83], v[108:109], off
	v_lshl_add_u64 v[108:109], s[56:57], 0, v[110:111]
	global_load_dwordx4 v[84:87], v[108:109], off
	v_lshl_add_u64 v[108:109], s[60:61], 0, v[110:111]
	global_load_dwordx4 v[88:91], v[108:109], off
	v_lshl_add_u64 v[108:109], s[66:67], 0, v[110:111]
	global_load_dwordx4 v[92:95], v[108:109], off
	v_lshl_add_u64 v[108:109], s[70:71], 0, v[110:111]
	global_load_dwordx4 v[96:99], v[108:109], off
	v_lshl_add_u64 v[108:109], s[72:73], 0, v[110:111]
	global_load_dwordx4 v[100:103], v[108:109], off
	v_lshl_add_u64 v[108:109], s[74:75], 0, v[110:111]
	global_load_dwordx4 v[104:107], v[108:109], off
	v_lshl_add_u64 v[108:109], s[76:77], 0, v[110:111]
	global_load_dwordx4 v[108:111], v[108:109], off
	s_waitcnt vmcnt(14)
	ds_write_b128 v10, v[0:3]
	s_waitcnt vmcnt(13)
; #define LAS __attribute__((address_space(3)))
; template <int dir>
; __device__ __forceinline__ void lru_pass(LAS unsigned char* lds, const Params& P, int b, int h, int q, bool dry) {
;     ...
;         for (int i = 0; i < 2; ++i) { const int idx = tid + i * NTHREADS, gate = idx >> 9, n = (idx >> 4) & 31, kc = idx & 15;
;             *(LAS u32x4*)(WB + (gate * 32 + n) * XC_PITCH + kc * 16) = *(const u32x4*)(LruW + ((size_t)((dir * 2 + gate) * 8 + h) * 128 + q * 32 + n) * 128 + kc * 8); }
;         const float br = -LOG2E * P.lru_ba[(dir * 8 + h) * 128 + chl], bi = -LOG2E * P.lru_bx[(dir * 8 + h) * 128 + chl];
;         const float lam = P.lru_lambda[dir * 1024 + ch];
;         const float cl = -8.0f * LOG2E * log1pf(__expf(-lam));
;         float carry = 0.f;
;         LruTile cur = lru_tile(Z, ZC, b, h, dir, 0);
;         u32x4 rows[11];
;         constexpr int NIN = dir == 0 ? 2 : 4;
;         u32x4 inr[NIN];
;         lru_load_rows(rows, cur, tr, cgp);
	ds_write_b128 v8, v[4:7]
	v_mul_f32_e32 v11, 0xbfb8aa3b, v16
	v_exp_f32_e32 v11, v11
	v_mul_lo_u32 v57, v39, s89
	v_mul_lo_u32 v58, v39, s30
	v_mul_lo_u32 v114, v64, s89
	v_add_f32_e32 v2, 1.0, v11
	v_add_f32_e32 v3, -1.0, v2
	v_frexp_mant_f32_e32 v4, v2
	v_cvt_f64_f32_e32 v[0:1], v2
	v_sub_f32_e32 v5, v3, v2
	v_frexp_exp_i32_f64_e32 v0, v[0:1]
	v_cmp_gt_f32_e32 vcc, s80, v4
	v_sub_f32_e32 v3, v11, v3
	v_add_f32_e32 v1, 1.0, v5
	v_subbrev_co_u32_e32 v0, vcc, 0, v0, vcc
	v_add_f32_e32 v1, v3, v1
	v_sub_u32_e32 v3, 0, v0
	v_ldexp_f32 v2, v2, v3
	v_ldexp_f32 v1, v1, v3
	v_add_f32_e32 v3, -1.0, v2
	v_add_f32_e32 v4, 1.0, v2
	v_add_f32_e32 v5, 1.0, v3
	v_add_f32_e32 v6, -1.0, v4
	v_sub_f32_e32 v5, v2, v5
	v_sub_f32_e32 v2, v2, v6
	v_add_f32_e32 v5, v1, v5
	v_add_f32_e32 v1, v1, v2
	v_add_f32_e32 v7, v4, v1
	v_rcp_f32_e32 v8, v7
	v_add_f32_e32 v2, v3, v5
	v_sub_f32_e32 v4, v7, v4
	v_sub_f32_e32 v3, v2, v3
	v_sub_f32_e32 v1, v1, v4
	v_mul_f32_e32 v4, v2, v8
	v_sub_f32_e32 v3, v5, v3
	v_mul_f32_e32 v5, v7, v4
	v_fma_f32 v10, v4, v7, -v5
	v_fmac_f32_e32 v10, v4, v1
	v_add_f32_e32 v16, v5, v10
	v_sub_f32_e32 v21, v2, v16
	v_sub_f32_e32 v2, v2, v21
	v_sub_f32_e32 v5, v16, v5
	v_sub_f32_e32 v2, v2, v16
	v_sub_f32_e32 v5, v5, v10
	v_add_f32_e32 v2, v3, v2
	v_add_f32_e32 v2, v5, v2
	v_add_f32_e32 v3, v21, v2
	v_mul_f32_e32 v5, v8, v3
	v_sub_f32_e32 v10, v21, v3
	v_mul_f32_e32 v16, v7, v5
	v_add_f32_e32 v2, v2, v10
	v_add_f32_e32 v10, v4, v5
	v_fma_f32 v7, v5, v7, -v16
	v_sub_f32_e32 v4, v10, v4
	v_fmac_f32_e32 v7, v5, v1
	v_sub_f32_e32 v1, v5, v4
	v_add_f32_e32 v4, v16, v7
	v_sub_f32_e32 v5, v4, v16
	v_sub_f32_e32 v16, v3, v4
	v_sub_f32_e32 v3, v3, v16
	v_sub_f32_e32 v3, v3, v4
	v_cvt_f32_i32_e32 v0, v0
	v_sub_f32_e32 v5, v5, v7
	v_add_f32_e32 v2, v2, v3
	v_add_f32_e32 v2, v5, v2
	v_add_f32_e32 v2, v16, v2
	v_mul_f32_e32 v2, v8, v2
	v_mul_f32_e32 v6, 0x3f317218, v0
	v_add_f32_e32 v1, v1, v2
	v_add_f32_e32 v2, v10, v1
	v_fma_f32 v5, v0, s81, -v6
	v_fmac_f32_e32 v5, 0xb102e308, v0
	v_sub_f32_e32 v0, v2, v10
	v_mul_f32_e32 v3, v2, v2
	v_sub_f32_e32 v0, v1, v0
	v_add_f32_e32 v1, v6, v5
	v_fmamk_f32 v4, v3, 0x3e9b6dac, v200
	v_sub_f32_e32 v6, v1, v6
	v_fmaak_f32 v4, v3, v4, 0x3f2aaada
	v_sub_f32_e32 v5, v5, v6
	v_ldexp_f32 v6, v2, 1
	v_mul_f32_e32 v2, v2, v3
	v_mul_f32_e32 v2, v2, v4
	v_add_f32_e32 v3, v6, v2
	v_sub_f32_e32 v4, v3, v6
	v_ldexp_f32 v0, v0, 1
	v_sub_f32_e32 v2, v2, v4
	v_add_f32_e32 v0, v0, v2
	v_add_f32_e32 v2, v3, v0
	v_sub_f32_e32 v3, v2, v3
	v_sub_f32_e32 v0, v0, v3
	v_add_f32_e32 v3, v1, v2
	v_sub_f32_e32 v4, v3, v1
	v_sub_f32_e32 v6, v3, v4
	v_sub_f32_e32 v1, v1, v6
	v_sub_f32_e32 v2, v2, v4
	v_add_f32_e32 v1, v2, v1
	v_add_f32_e32 v2, v5, v0
	v_sub_f32_e32 v4, v2, v5
	v_add_f32_e32 v1, v2, v1
	v_sub_f32_e32 v6, v2, v4
	v_add_f32_e32 v2, v3, v1
	v_sub_f32_e32 v5, v5, v6
	v_sub_f32_e32 v0, v0, v4
	v_sub_f32_e32 v3, v2, v3
	v_add_f32_e32 v0, v0, v5
	v_sub_f32_e32 v1, v1, v3
	v_add_f32_e32 v0, v0, v1
	v_add_f32_e32 v0, v2, v0
	v_cmp_neq_f32_e32 vcc, s91, v11
	v_mov_b32_e32 v1, v65
	v_mul_lo_u32 v115, v64, s30
	v_cndmask_b32_e32 v0, v201, v0, vcc
	v_cmp_ngt_f32_e32 vcc, -1.0, v11
	v_mul_lo_u32 v206, v39, s87
	v_mul_lo_u32 v210, v64, s87
	v_cndmask_b32_e32 v0, v202, v0, vcc
	v_cmp_neq_f32_e32 vcc, -1.0, v11
	v_ashrrev_i32_e32 v39, 31, v38
	v_sub_u32_e32 v41, 0xfe, v37
	v_cndmask_b32_e32 v0, v203, v0, vcc
	v_cmp_lt_f32_e64 vcc, |v11|, s92
	v_mul_lo_u32 v59, v41, s89
	v_mul_lo_u32 v60, v41, s30
	v_cndmask_b32_e32 v6, v0, v11, vcc
	v_lshlrev_b32_e32 v2, 4, v32
	v_and_b32_e32 v2, 0x70, v2
	v_lshlrev_b32_e32 v1, 2, v15
	v_add_u32_e32 v45, s95, v2
	v_or3_b32 v2, v19, v20, s0
	s_and_b32 s0, s4, 0x3fffffc0
	v_add_u32_e32 v161, s94, v1
	s_cmp_eq_u32 s6, 7
	v_lshl_add_u32 v254, s0, 2, v161
	s_cselect_b64 s[0:1], -1, 0
	s_cmp_eq_u32 s6, 6
	s_cselect_b64 s[16:17], -1, 0
	s_cmp_eq_u32 s6, 5
	s_cselect_b64 s[4:5], -1, 0
	s_cmp_eq_u32 s6, 4
	s_cselect_b64 s[8:9], -1, 0
	s_cmp_eq_u32 s6, 3
	s_cselect_b64 s[10:11], -1, 0
	s_cmp_eq_u32 s6, 2
	s_cselect_b64 s[12:13], -1, 0
	s_cmp_eq_u32 s6, 1
	s_cselect_b64 s[14:15], -1, 0
	s_lshl_b32 s6, s25, 7
	s_and_b32 s6, s6, 0xe00
	s_lshl_b32 s7, s29, 7
	s_or_b32 s6, s7, s6
	s_add_u32 s6, s6, s44
	v_add_u32_e32 v50, s95, v1
	v_add_u32_e32 v1, 0x400, v32
	s_addc_u32 s7, 0, s45
	v_ashrrev_i32_e32 v40, 3, v1
	v_add_u32_e32 v1, 0x600, v32
	v_and_b32_e32 v32, 7, v32
	s_add_u32 s18, s84, s46
	v_lshlrev_b32_e32 v64, 4, v32
	v_lshl_or_b32 v32, v33, 10, v34
	v_mov_b32_e32 v33, v65
	s_addc_u32 s19, s85, s47
	v_lshl_add_u64 v[144:145], v[32:33], 1, s[18:19]
	v_lshlrev_b64 v[32:33], 12, v[38:39]
	v_lshl_add_u64 v[32:33], s[6:7], 0, v[32:33]
	v_mul_lo_u32 v207, v41, s87
	v_lshl_add_u64 v[32:33], v[32:33], 0, v[64:65]
	v_ashrrev_i32_e32 v41, 31, v40
	v_or_b32_e32 v43, 2, v37
	v_lshl_add_u64 v[252:253], s[42:43], 0, v[32:33]
	v_lshlrev_b64 v[32:33], 12, v[40:41]
	v_ashrrev_i32_e32 v42, 3, v1
	v_sub_u32_e32 v43, 0xff, v43
	v_or_b32_e32 v63, 3, v37
	v_or_b32_e32 v66, 5, v37
	v_or_b32_e32 v67, 6, v37
	v_or_b32_e32 v120, 7, v37
	v_or_b32_e32 v123, 8, v37
	v_or_b32_e32 v126, 9, v37
	v_or_b32_e32 v129, 10, v37
	v_or_b32_e32 v132, 11, v37
	v_or_b32_e32 v135, 12, v37
	v_or_b32_e32 v142, 13, v37
	v_or_b32_e32 v143, 14, v37
	v_or_b32_e32 v37, 15, v37
	v_lshl_add_u64 v[32:33], s[6:7], 0, v[32:33]
	v_mul_lo_u32 v61, v43, s89
	v_mul_lo_u32 v62, v43, s30
	v_sub_u32_e32 v37, 0xff, v37
	v_mul_lo_u32 v208, v43, s87
	v_lshl_add_u64 v[32:33], v[32:33], 0, v[64:65]
	v_ashrrev_i32_e32 v43, 31, v42
	v_sub_u32_e32 v2, 0xff, v2
	v_mul_lo_u32 v204, v37, s89
	v_mul_lo_u32 v205, v37, s30
	v_mul_lo_u32 v221, v37, s87
	v_ashrrev_i32_e32 v37, 31, v36
	v_lshl_add_u64 v[154:155], s[42:43], 0, v[32:33]
	v_lshlrev_b64 v[32:33], 12, v[42:43]
	v_mul_lo_u32 v2, v2, s89
	v_mul_lo_u32 v53, v36, s30
	v_sub_u32_e32 v63, 0xff, v63
	v_sub_u32_e32 v66, 0xff, v66
	v_sub_u32_e32 v67, 0xff, v67
	v_sub_u32_e32 v120, 0xff, v120
	v_sub_u32_e32 v123, 0xff, v123
	v_sub_u32_e32 v126, 0xff, v126
	v_lshlrev_b64 v[36:37], 12, v[36:37]
	v_lshl_add_u64 v[32:33], s[6:7], 0, v[32:33]
	v_lshlrev_b32_e32 v35, 5, v12
	v_add_u32_e32 v47, 0, v2
	v_mov_b32_e32 v2, s88
	v_lshl_add_u32 v49, v17, 1, 0
	v_lshl_add_u32 v51, v15, 1, s86
	v_mul_lo_u32 v112, v63, s89
	v_mul_lo_u32 v113, v63, s30
	v_mul_lo_u32 v116, v66, s89
	v_mul_lo_u32 v117, v66, s30
	v_mul_lo_u32 v118, v67, s89
	v_mul_lo_u32 v119, v67, s30
	v_mul_lo_u32 v121, v120, s89
	v_mul_lo_u32 v122, v120, s30
	v_mul_lo_u32 v124, v123, s89
	v_mul_lo_u32 v125, v123, s30
	v_mul_lo_u32 v127, v126, s89
	v_mul_lo_u32 v128, v126, s30
	v_sub_u32_e32 v129, 0xff, v129
	v_sub_u32_e32 v132, 0xff, v132
	v_sub_u32_e32 v135, 0xff, v135
	v_sub_u32_e32 v142, 0xff, v142
	v_sub_u32_e32 v143, 0xff, v143
	v_mul_lo_u32 v211, v66, s87
	v_mul_lo_u32 v212, v67, s87
	v_mul_lo_u32 v120, v120, s87
	v_mul_lo_u32 v123, v123, s87
	v_mul_lo_u32 v126, v126, s87
	v_lshl_add_u64 v[36:37], s[6:7], 0, v[36:37]
	v_lshl_add_u64 v[32:33], v[32:33], 0, v[64:65]
	v_mov_b32_e32 v66, v65
	v_mov_b32_e32 v67, v65
	s_waitcnt vmcnt(12)
; template <int dir>
; __device__ __forceinline__ void lru_pass(LAS unsigned char* lds, const Params& P, int b, int h, int q, bool dry) {
;     ...
;         const float br = -LOG2E * P.lru_ba[(dir * 8 + h) * 128 + chl], bi = -LOG2E * P.lru_bx[(dir * 8 + h) * 128 + chl];
;         const float lam = P.lru_lambda[dir * 1024 + ch];
;         const float cl = -8.0f * LOG2E * log1pf(__expf(-lam));
;         float carry = 0.f;
;         LruTile cur = lru_tile(Z, ZC, b, h, dir, 0);
;         u32x4 rows[11];
;         constexpr int NIN = dir == 0 ? 2 : 4;
;         u32x4 inr[NIN];
;         lru_load_rows(rows, cur, tr, cgp);
; #pragma unroll
;         for (int i = 0; i < NIN; ++i) inr[i] = (u32x4){0u, 0u, 0u, 0u};
;         int t0_prev = 0;
;     ...
;             for (int v = 0; v < 16; ++v) { zr[v] = br; zi[v] = bi; }
	v_mul_f32_e32 v0, 0xbfb8aa3b, v14
	s_waitcnt vmcnt(11)
	v_mul_f32_e32 v16, 0xbfb8aa3b, v9
	v_mad_u32_u24 v48, v15, s89, v2
	v_mul_lo_u32 v54, v38, s30
	v_mul_lo_u32 v55, v40, s30
	v_mul_lo_u32 v56, v42, s30
	v_ashrrev_i32_e32 v138, 2, v13
	v_mul_lo_u32 v130, v129, s89
	v_mul_lo_u32 v131, v129, s30
	v_mul_lo_u32 v133, v132, s89
	v_mul_lo_u32 v134, v132, s30
	v_mul_lo_u32 v146, v135, s89
	v_mul_lo_u32 v147, v135, s30
	v_mul_lo_u32 v148, v142, s89
	v_mul_lo_u32 v149, v142, s30
	v_mul_lo_u32 v162, v143, s89
	v_mul_lo_u32 v163, v143, s30
	v_mul_lo_u32 v63, v63, s87
	v_mul_lo_u32 v129, v129, s87
	v_mul_lo_u32 v132, v132, s87
	v_mul_lo_u32 v135, v135, s87
	v_mul_lo_u32 v219, v142, s87
	v_mul_lo_u32 v220, v143, s87
	v_lshl_add_u64 v[36:37], v[36:37], 0, v[64:65]
	v_lshl_add_u64 v[150:151], s[42:43], 0, v[32:33]
	v_mov_b32_e32 v64, v65
	v_add_u32_e32 v32, 0, v35
	v_add_u32_e32 v180, v49, v112
	v_add_u32_e32 v181, v50, v113
	v_add_u32_e32 v182, v49, v114
	v_add_u32_e32 v183, v50, v115
	v_add_u32_e32 v184, v49, v116
	v_add_u32_e32 v185, v50, v117
	v_add_u32_e32 v186, v49, v118
	v_add_u32_e32 v187, v50, v119
	v_add_u32_e32 v188, v49, v121
	v_add_u32_e32 v189, v50, v122
	v_add_u32_e32 v190, v49, v124
	v_add_u32_e32 v191, v50, v125
	v_add_u32_e32 v192, v49, v127
	v_add_u32_e32 v213, v51, v120
	v_add_u32_e32 v214, v51, v123
	v_add_u32_e32 v215, v51, v126
	v_mov_b64_e32 v[114:115], v[66:67]
	v_mov_b64_e32 v[118:119], v[66:67]
	v_mov_b64_e32 v[122:123], v[66:67]
	v_mov_b64_e32 v[126:127], v[66:67]
	s_mov_b32 s78, 0
	v_mov_b32_e32 v156, 0xff800000
	v_mul_f32_e32 v159, 0xc138aa3b, v6
	v_cmp_eq_u32_e32 vcc, 0, v18
	v_mul_lo_u32 v164, v140, s87
	v_ashrrev_i32_e32 v141, 31, v140
	v_mul_lo_u32 v152, v138, s87
	v_ashrrev_i32_e32 v139, 31, v138
	v_mov_b32_e32 v1, v0
	v_mov_b32_e32 v2, v0
	v_mov_b32_e32 v3, v0
	v_mov_b32_e32 v4, v0
	v_mov_b32_e32 v5, v0
	v_mov_b32_e32 v6, v0
	v_mov_b32_e32 v7, v0
	v_mov_b32_e32 v8, v0
	v_mov_b32_e32 v9, v0
	v_mov_b32_e32 v10, v0
	v_mov_b32_e32 v11, v0
	v_mov_b32_e32 v12, v0
	v_mov_b32_e32 v13, v0
	v_mov_b32_e32 v14, v0
	v_mov_b32_e32 v15, v0
	v_mov_b32_e32 v17, v16
	v_mov_b32_e32 v18, v16
	v_mov_b32_e32 v19, v16
	v_mov_b32_e32 v20, v16
	v_mov_b32_e32 v21, v16
	v_mov_b32_e32 v22, v16
	v_mov_b32_e32 v23, v16
	v_mov_b32_e32 v24, v16
	v_mov_b32_e32 v25, v16
	v_mov_b32_e32 v26, v16
	v_mov_b32_e32 v27, v16
	v_mov_b32_e32 v28, v16
	v_mov_b32_e32 v29, v16
	v_mov_b32_e32 v30, v16
	v_mov_b32_e32 v31, v16
	v_lshl_add_u64 v[142:143], s[42:43], 0, v[36:37]
	s_movk_i32 s28, 0x100
	v_mov_b32_e32 v222, 0
	s_mov_b64 s[44:45], 0
	s_movk_i32 s25, 0x700
	v_add_u32_e32 v165, 0x15c00, v32
	v_add_u32_e32 v166, v44, v52
	v_add_u32_e32 v168, v45, v53
	v_add_u32_e32 v169, v45, v54
	v_add_u32_e32 v170, v45, v55
	v_add_u32_e32 v171, v45, v56
	v_add_u32_e32 v172, v47, v46
	v_add_u32_e32 v173, v48, v46
	v_add_u32_e32 v174, v49, v57
	v_add_u32_e32 v175, v50, v58
	v_add_u32_e32 v176, v49, v59
	v_add_u32_e32 v177, v50, v60
	v_add_u32_e32 v178, v49, v61
	v_add_u32_e32 v179, v50, v62
	v_add_u32_e32 v193, v50, v128
	v_add_u32_e32 v194, v49, v130
	v_add_u32_e32 v195, v50, v131
	v_add_u32_e32 v196, v49, v133
	v_add_u32_e32 v197, v50, v134
	v_add_u32_e32 v198, v49, v146
	v_add_u32_e32 v199, v50, v147
	v_add_u32_e32 v200, v49, v148
	v_add_u32_e32 v201, v50, v149
	v_add_u32_e32 v202, v49, v162
	v_add_u32_e32 v203, v50, v163
	v_add_u32_e32 v204, v49, v204
	v_add_u32_e32 v205, v50, v205
	v_add_u32_e32 v206, v51, v206
	v_add_u32_e32 v207, v51, v207
	v_add_u32_e32 v208, v51, v208
	v_add_u32_e32 v209, v51, v63
	v_add_u32_e32 v210, v51, v210
	v_add_u32_e32 v211, v51, v211
	v_add_u32_e32 v212, v51, v212
	v_add_u32_e32 v216, v51, v129
	v_add_u32_e32 v217, v51, v132
	v_add_u32_e32 v218, v51, v135
	v_add_u32_e32 v219, v51, v219
	v_add_u32_e32 v220, v51, v220
	v_add_u32_e32 v221, v51, v221
	v_mov_b64_e32 v[112:113], v[64:65]
	v_mov_b64_e32 v[116:117], v[64:65]
	v_mov_b64_e32 v[120:121], v[64:65]
	v_mov_b64_e32 v[124:125], v[64:65]
	s_mov_b32 s46, 0
	s_mov_b32 s29, 0
